# hyena st0 spectrum stores hand-written: mirrored partners read as one contiguous 32-byte LDS block (index identity), reads one iteration ahead
# speedup vs baseline: 1.1849x; 1.0024x over previous
; HD float2 cmul(float2 a, float2 b){ return make_float2(a.x*b.x - a.y*b.y, a.x*b.y + a.y*b.x); }
; template<bool INV, int LQ, bool BARRIER=true>
; HD void fft_pass(float2* Z, const float2* twA, const float2* twB, int tid){
;     ...
;     int j=tid&(q-1); int base0=((tid>>LQ)<<(LQ+2))+j;
;     float2 w1=make_float2(1.f,0.f), w2=w1, w3=w1;
;     if (LQ>0){ int k=j*tws; w1=cmul(twA[k>>6],twB[k&63]); w2=cmul(w1,w1); w3=cmul(w2,w1); }
;     _Pragma("unroll") for (int i=0;i<8;++i){ int base=base0+i*2048; bf4c<INV,(LQ==0)>(Z,base,base+q,base+2*q,base+3*q,w1,w2,w3); }
;   }
;   if (BARRIER) __syncthreads(); else asm volatile("s_waitcnt lgkmcnt(0)" ::: "memory");
; __device__ __forceinline__ void phase_hyena(KP kp_, int hf){ asm volatile("" : "+s"(kp_)); const Params p=load_params(kp_);
;     ...
;         fft_pass<false,0>(Z,twA,twB,tid);
.LBB0_1344:
	s_and_b64 vcc, exec, s[12:13]
	s_cbranch_vccz .LBB0_1198
	ds_read_b128 v[0:3], v203
	ds_read_b128 v[4:7], v203 offset:16
	s_mov_b32 s12, 0.5
	s_mov_b32 s13, -0.5
	s_waitcnt lgkmcnt(0)
	v_pk_add_f32 v[12:13], v[0:1], v[4:5]
	v_pk_add_f32 v[14:15], v[2:3], v[6:7]
	v_pk_add_f32 v[0:1], v[0:1], v[4:5] neg_lo:[0,1] neg_hi:[0,1]
	v_pk_add_f32 v[2:3], v[2:3], v[6:7] neg_lo:[0,1] neg_hi:[0,1]
	v_pk_add_f32 v[8:9], v[12:13], v[14:15]
	v_pk_add_f32 v[4:5], v[0:1], v[2:3] op_sel:[0,1] op_sel_hi:[1,0]
	v_pk_add_f32 v[2:3], v[0:1], v[2:3] op_sel:[0,1] op_sel_hi:[1,0] neg_lo:[0,1] neg_hi:[0,1]
	v_mov_b32_e32 v10, v4
	v_mov_b32_e32 v11, v3
	v_pk_add_f32 v[0:1], v[12:13], v[14:15] neg_lo:[0,1] neg_hi:[0,1]
	v_mov_b32_e32 v3, v5
	ds_write_b128 v203, v[8:11]
	ds_write_b128 v203, v[0:3] offset:16
	ds_read_b128 v[0:3], v203 offset:16384
	ds_read_b128 v[4:7], v203 offset:16400
	s_waitcnt lgkmcnt(0)
	v_pk_add_f32 v[12:13], v[0:1], v[4:5]
	v_pk_add_f32 v[14:15], v[2:3], v[6:7]
	v_pk_add_f32 v[0:1], v[0:1], v[4:5] neg_lo:[0,1] neg_hi:[0,1]
	v_pk_add_f32 v[2:3], v[2:3], v[6:7] neg_lo:[0,1] neg_hi:[0,1]
	v_pk_add_f32 v[8:9], v[12:13], v[14:15]
	v_pk_add_f32 v[4:5], v[0:1], v[2:3] op_sel:[0,1] op_sel_hi:[1,0]
	v_pk_add_f32 v[2:3], v[0:1], v[2:3] op_sel:[0,1] op_sel_hi:[1,0] neg_lo:[0,1] neg_hi:[0,1]
	v_mov_b32_e32 v10, v4
	v_mov_b32_e32 v11, v3
	v_pk_add_f32 v[0:1], v[12:13], v[14:15] neg_lo:[0,1] neg_hi:[0,1]
	v_mov_b32_e32 v3, v5
	ds_write_b128 v203, v[8:11] offset:16384
	ds_write_b128 v203, v[0:3] offset:16400
	ds_read_b128 v[0:3], v203 offset:32768
	ds_read_b128 v[4:7], v203 offset:32784
	s_waitcnt lgkmcnt(0)
	v_pk_add_f32 v[12:13], v[0:1], v[4:5]
	v_pk_add_f32 v[14:15], v[2:3], v[6:7]
	v_pk_add_f32 v[0:1], v[0:1], v[4:5] neg_lo:[0,1] neg_hi:[0,1]
	v_pk_add_f32 v[2:3], v[2:3], v[6:7] neg_lo:[0,1] neg_hi:[0,1]
	v_pk_add_f32 v[8:9], v[12:13], v[14:15]
	v_pk_add_f32 v[4:5], v[0:1], v[2:3] op_sel:[0,1] op_sel_hi:[1,0]
	v_pk_add_f32 v[2:3], v[0:1], v[2:3] op_sel:[0,1] op_sel_hi:[1,0] neg_lo:[0,1] neg_hi:[0,1]
	v_mov_b32_e32 v10, v4
	v_mov_b32_e32 v11, v3
	v_pk_add_f32 v[0:1], v[12:13], v[14:15] neg_lo:[0,1] neg_hi:[0,1]
	v_mov_b32_e32 v3, v5
	ds_write_b128 v203, v[8:11] offset:32768
	ds_write_b128 v203, v[0:3] offset:32784
	ds_read_b128 v[0:3], v203 offset:49152
	ds_read_b128 v[4:7], v203 offset:49168
	s_waitcnt lgkmcnt(0)
	v_pk_add_f32 v[12:13], v[0:1], v[4:5]
	v_pk_add_f32 v[14:15], v[2:3], v[6:7]
	v_pk_add_f32 v[0:1], v[0:1], v[4:5] neg_lo:[0,1] neg_hi:[0,1]
	v_pk_add_f32 v[2:3], v[2:3], v[6:7] neg_lo:[0,1] neg_hi:[0,1]
	v_pk_add_f32 v[8:9], v[12:13], v[14:15]
	v_pk_add_f32 v[4:5], v[0:1], v[2:3] op_sel:[0,1] op_sel_hi:[1,0]
	v_pk_add_f32 v[2:3], v[0:1], v[2:3] op_sel:[0,1] op_sel_hi:[1,0] neg_lo:[0,1] neg_hi:[0,1]
	v_mov_b32_e32 v10, v4
	v_mov_b32_e32 v11, v3
	v_pk_add_f32 v[0:1], v[12:13], v[14:15] neg_lo:[0,1] neg_hi:[0,1]
	v_mov_b32_e32 v3, v5
	ds_write_b128 v203, v[8:11] offset:49152
	ds_write_b128 v203, v[0:3] offset:49168
	ds_read_b128 v[0:3], v204
	ds_read_b128 v[4:7], v205
	s_waitcnt lgkmcnt(0)
	v_pk_add_f32 v[12:13], v[0:1], v[4:5]
	v_pk_add_f32 v[14:15], v[2:3], v[6:7]
	v_pk_add_f32 v[0:1], v[0:1], v[4:5] neg_lo:[0,1] neg_hi:[0,1]
	v_pk_add_f32 v[2:3], v[2:3], v[6:7] neg_lo:[0,1] neg_hi:[0,1]
	v_pk_add_f32 v[8:9], v[12:13], v[14:15]
	v_pk_add_f32 v[4:5], v[0:1], v[2:3] op_sel:[0,1] op_sel_hi:[1,0]
	v_pk_add_f32 v[2:3], v[0:1], v[2:3] op_sel:[0,1] op_sel_hi:[1,0] neg_lo:[0,1] neg_hi:[0,1]
	v_mov_b32_e32 v10, v4
	v_mov_b32_e32 v11, v3
	v_pk_add_f32 v[0:1], v[12:13], v[14:15] neg_lo:[0,1] neg_hi:[0,1]
	v_mov_b32_e32 v3, v5
	ds_write_b128 v204, v[8:11]
	ds_write_b128 v205, v[0:3]
	ds_read_b128 v[0:3], v206
	ds_read_b128 v[4:7], v207
	s_waitcnt lgkmcnt(0)
	v_pk_add_f32 v[12:13], v[0:1], v[4:5]
	v_pk_add_f32 v[14:15], v[2:3], v[6:7]
	v_pk_add_f32 v[0:1], v[0:1], v[4:5] neg_lo:[0,1] neg_hi:[0,1]
	v_pk_add_f32 v[2:3], v[2:3], v[6:7] neg_lo:[0,1] neg_hi:[0,1]
	v_pk_add_f32 v[8:9], v[12:13], v[14:15]
	v_pk_add_f32 v[4:5], v[0:1], v[2:3] op_sel:[0,1] op_sel_hi:[1,0]
	v_pk_add_f32 v[2:3], v[0:1], v[2:3] op_sel:[0,1] op_sel_hi:[1,0] neg_lo:[0,1] neg_hi:[0,1]
	v_mov_b32_e32 v10, v4
	v_mov_b32_e32 v11, v3
	v_pk_add_f32 v[0:1], v[12:13], v[14:15] neg_lo:[0,1] neg_hi:[0,1]
	v_mov_b32_e32 v3, v5
	ds_write_b128 v206, v[8:11]
	ds_write_b128 v207, v[0:3]
	ds_read_b128 v[0:3], v208
	ds_read_b128 v[4:7], v209
	s_waitcnt lgkmcnt(0)
	v_pk_add_f32 v[12:13], v[0:1], v[4:5]
	v_pk_add_f32 v[14:15], v[2:3], v[6:7]
	v_pk_add_f32 v[0:1], v[0:1], v[4:5] neg_lo:[0,1] neg_hi:[0,1]
	v_pk_add_f32 v[2:3], v[2:3], v[6:7] neg_lo:[0,1] neg_hi:[0,1]
	v_pk_add_f32 v[8:9], v[12:13], v[14:15]
	v_pk_add_f32 v[4:5], v[0:1], v[2:3] op_sel:[0,1] op_sel_hi:[1,0]
	v_pk_add_f32 v[2:3], v[0:1], v[2:3] op_sel:[0,1] op_sel_hi:[1,0] neg_lo:[0,1] neg_hi:[0,1]
	v_mov_b32_e32 v10, v4
	v_mov_b32_e32 v11, v3
	v_pk_add_f32 v[0:1], v[12:13], v[14:15] neg_lo:[0,1] neg_hi:[0,1]
	v_mov_b32_e32 v3, v5
	ds_write_b128 v208, v[8:11]
	ds_write_b128 v209, v[0:3]
	ds_read_b128 v[0:3], v210
	ds_read_b128 v[4:7], v211
	s_waitcnt lgkmcnt(0)
	v_pk_add_f32 v[12:13], v[0:1], v[4:5]
	v_pk_add_f32 v[14:15], v[2:3], v[6:7]
	v_pk_add_f32 v[0:1], v[0:1], v[4:5] neg_lo:[0,1] neg_hi:[0,1]
	v_pk_add_f32 v[2:3], v[2:3], v[6:7] neg_lo:[0,1] neg_hi:[0,1]
	v_pk_add_f32 v[8:9], v[12:13], v[14:15]
	v_pk_add_f32 v[4:5], v[0:1], v[2:3] op_sel:[0,1] op_sel_hi:[1,0]
	v_pk_add_f32 v[2:3], v[0:1], v[2:3] op_sel:[0,1] op_sel_hi:[1,0] neg_lo:[0,1] neg_hi:[0,1]
	v_pk_add_f32 v[0:1], v[12:13], v[14:15] neg_lo:[0,1] neg_hi:[0,1]
	v_mov_b32_e32 v11, v3
	v_mov_b32_e32 v3, v5
	v_mov_b32_e32 v10, v4
	ds_write_b128 v211, v[0:3]
	v_mul_f32_e32 v2, 0.5, v78
	v_pk_mul_f32 v[0:1], v[78:79], s[12:13] op_sel:[1,0]
	s_mov_b32 s12, 0
	v_mov_b32_e32 v3, v203
	ds_write_b128 v210, v[8:11]
	s_waitcnt lgkmcnt(0)
	s_barrier
; HD int rev4_14(int p){ unsigned r = __brev((unsigned)p) >> 18; return (int)(((r & 0x2AAAu) >> 1) | ((r & 0x1555u) << 1)); }
; __device__ __forceinline__ void phase_hyena(KP kp_, int hf){ asm volatile("" : "+s"(kp_)); const Params p=load_params(kp_);
;     ...
;     _Pragma("unroll 2") for (int i=0;i<8;++i){ int q0=(tid+512*i)*4; u32x4 h0w, h1w;
;       _Pragma("unroll") for (int m=0;m<4;++m){ int q=q0+m; int k=rev4_14(q);
;         float2 Fk=Z[q], Fn=Z[rev4_14((16384-k)&16383)];
;         f16x2 h0v={(_Float16)(0.5f*nrm0*(Fk.x+Fn.x)),(_Float16)(0.5f*nrm0*(Fk.y-Fn.y))};
;         f16x2 h1v={(_Float16)(0.5f*nrm1*(Fk.y+Fn.y)),(_Float16)(-0.5f*nrm1*(Fk.x-Fn.x))};
;         unsigned u0=__builtin_bit_cast(unsigned,h0v), u1=__builtin_bit_cast(unsigned,h1v);
;         h0w[m]=u0; h1w[m]=u1; }
;       *(u32x4*)(H0p+q0)=h0w; *(u32x4*)(H1p+q0)=h1w; }
	v_lshlrev_b32_e32 v70, 5, v154
	v_add_u32_e32 v71, 0x10000, v70
	v_lshlrev_b32_e32 v72, 4, v154
	v_cmp_eq_u32_e64 s[12:13], 0, v154
	v_mov_b32_e32 v68, v154
	v_bfrev_b32_e32 v66, v68
	v_lshrrev_b32_e32 v66, 20, v66
	v_and_b32_e32 v67, 0xaaa, v66
	v_and_b32_e32 v66, 0x555, v66
	v_lshrrev_b32_e32 v67, 1, v67
	v_lshl_or_b32 v69, v66, 1, v67
	v_sub_u32_e32 v69, 0x1000, v69
	v_and_b32_e32 v69, 0xfff, v69
	v_bfrev_b32_e32 v66, v69
	v_lshrrev_b32_e32 v66, 20, v66
	v_and_b32_e32 v67, 0xaaa, v66
	v_and_b32_e32 v66, 0x555, v66
	v_lshrrev_b32_e32 v67, 1, v67
	v_lshl_or_b32 v68, v66, 1, v67
	v_lshlrev_b32_e32 v73, 5, v68
	ds_read_b128 v[4:7], v70 offset:0
	ds_read_b128 v[8:11], v70 offset:16
	ds_read_b128 v[12:15], v73
	ds_read_b128 v[16:19], v73 offset:16
	v_add_u32_e32 v68, 0x200, v154
	v_bfrev_b32_e32 v66, v68
	v_lshrrev_b32_e32 v66, 20, v66
	v_and_b32_e32 v67, 0xaaa, v66
	v_and_b32_e32 v66, 0x555, v66
	v_lshrrev_b32_e32 v67, 1, v67
	v_lshl_or_b32 v69, v66, 1, v67
	v_sub_u32_e32 v69, 0x1000, v69
	v_and_b32_e32 v69, 0xfff, v69
	v_bfrev_b32_e32 v66, v69
	v_lshrrev_b32_e32 v66, 20, v66
	v_and_b32_e32 v67, 0xaaa, v66
	v_and_b32_e32 v66, 0x555, v66
	v_lshrrev_b32_e32 v67, 1, v67
	v_lshl_or_b32 v68, v66, 1, v67
	v_lshlrev_b32_e32 v73, 5, v68
	ds_read_b128 v[20:23], v70 offset:16384
	ds_read_b128 v[24:27], v70 offset:16400
	ds_read_b128 v[58:61], v73
	ds_read_b128 v[62:65], v73 offset:16
	s_waitcnt lgkmcnt(4)
	v_cndmask_b32_e64 v112, v18, v12, s[12:13]
	v_cndmask_b32_e64 v113, v19, v13, s[12:13]
	v_cndmask_b32_e64 v114, v16, v18, s[12:13]
	v_cndmask_b32_e64 v115, v17, v19, s[12:13]
	v_cndmask_b32_e64 v116, v14, v16, s[12:13]
	v_cndmask_b32_e64 v117, v15, v17, s[12:13]
	v_cndmask_b32_e64 v118, v12, v14, s[12:13]
	v_cndmask_b32_e64 v119, v13, v15, s[12:13]
	v_pk_add_f32 v[104:105], v[4:5], v[112:113]
	v_pk_add_f32 v[106:107], v[4:5], v[112:113] neg_lo:[0,1] neg_hi:[0,1]
	v_mul_f32_e32 v108, v2, v104
	v_mul_f32_e32 v109, v2, v107
	v_mul_f32_e32 v110, v0, v105
	v_mul_f32_e32 v111, v1, v106
	v_cvt_pk_f16_f32 v82, v108, v109
	v_cvt_pk_f16_f32 v100, v110, v111
	v_pk_add_f32 v[104:105], v[6:7], v[114:115]
	v_pk_add_f32 v[106:107], v[6:7], v[114:115] neg_lo:[0,1] neg_hi:[0,1]
	v_mul_f32_e32 v108, v2, v104
	v_mul_f32_e32 v109, v2, v107
	v_mul_f32_e32 v110, v0, v105
	v_mul_f32_e32 v111, v1, v106
	v_cvt_pk_f16_f32 v83, v108, v109
	v_cvt_pk_f16_f32 v101, v110, v111
	v_pk_add_f32 v[104:105], v[8:9], v[116:117]
	v_pk_add_f32 v[106:107], v[8:9], v[116:117] neg_lo:[0,1] neg_hi:[0,1]
	v_mul_f32_e32 v108, v2, v104
	v_mul_f32_e32 v109, v2, v107
	v_mul_f32_e32 v110, v0, v105
	v_mul_f32_e32 v111, v1, v106
	v_cvt_pk_f16_f32 v84, v108, v109
	v_cvt_pk_f16_f32 v102, v110, v111
	v_pk_add_f32 v[104:105], v[10:11], v[118:119]
	v_pk_add_f32 v[106:107], v[10:11], v[118:119] neg_lo:[0,1] neg_hi:[0,1]
	v_mul_f32_e32 v108, v2, v104
	v_mul_f32_e32 v109, v2, v107
	v_mul_f32_e32 v110, v0, v105
	v_mul_f32_e32 v111, v1, v106
	v_cvt_pk_f16_f32 v85, v108, v109
	v_cvt_pk_f16_f32 v103, v110, v111
	v_mov_b32_e32 v74, v72
	global_store_dwordx4 v74, v[82:85], s[76:77]
	global_store_dwordx4 v74, v[100:103], s[78:79]
	s_nop 1
	v_add_u32_e32 v68, 0x400, v154
	v_bfrev_b32_e32 v66, v68
	v_lshrrev_b32_e32 v66, 20, v66
	v_and_b32_e32 v67, 0xaaa, v66
	v_and_b32_e32 v66, 0x555, v66
	v_lshrrev_b32_e32 v67, 1, v67
	v_lshl_or_b32 v69, v66, 1, v67
	v_sub_u32_e32 v69, 0x1000, v69
	v_and_b32_e32 v69, 0xfff, v69
	v_bfrev_b32_e32 v66, v69
	v_lshrrev_b32_e32 v66, 20, v66
	v_and_b32_e32 v67, 0xaaa, v66
	v_and_b32_e32 v66, 0x555, v66
	v_lshrrev_b32_e32 v67, 1, v67
	v_lshl_or_b32 v68, v66, 1, v67
	v_lshlrev_b32_e32 v73, 5, v68
	ds_read_b128 v[4:7], v70 offset:32768
	ds_read_b128 v[8:11], v70 offset:32784
	ds_read_b128 v[12:15], v73
	ds_read_b128 v[16:19], v73 offset:16
	s_waitcnt lgkmcnt(4)
	v_pk_add_f32 v[104:105], v[20:21], v[64:65]
	v_pk_add_f32 v[106:107], v[20:21], v[64:65] neg_lo:[0,1] neg_hi:[0,1]
	v_mul_f32_e32 v108, v2, v104
	v_mul_f32_e32 v109, v2, v107
	v_mul_f32_e32 v110, v0, v105
	v_mul_f32_e32 v111, v1, v106
	v_cvt_pk_f16_f32 v82, v108, v109
	v_cvt_pk_f16_f32 v100, v110, v111
	v_pk_add_f32 v[104:105], v[22:23], v[62:63]
	v_pk_add_f32 v[106:107], v[22:23], v[62:63] neg_lo:[0,1] neg_hi:[0,1]
	v_mul_f32_e32 v108, v2, v104
	v_mul_f32_e32 v109, v2, v107
	v_mul_f32_e32 v110, v0, v105
	v_mul_f32_e32 v111, v1, v106
	v_cvt_pk_f16_f32 v83, v108, v109
	v_cvt_pk_f16_f32 v101, v110, v111
	v_pk_add_f32 v[104:105], v[24:25], v[60:61]
	v_pk_add_f32 v[106:107], v[24:25], v[60:61] neg_lo:[0,1] neg_hi:[0,1]
	v_mul_f32_e32 v108, v2, v104
	v_mul_f32_e32 v109, v2, v107
	v_mul_f32_e32 v110, v0, v105
	v_mul_f32_e32 v111, v1, v106
	v_cvt_pk_f16_f32 v84, v108, v109
	v_cvt_pk_f16_f32 v102, v110, v111
	v_pk_add_f32 v[104:105], v[26:27], v[58:59]
	v_pk_add_f32 v[106:107], v[26:27], v[58:59] neg_lo:[0,1] neg_hi:[0,1]
	v_mul_f32_e32 v108, v2, v104
	v_mul_f32_e32 v109, v2, v107
	v_mul_f32_e32 v110, v0, v105
	v_mul_f32_e32 v111, v1, v106
	v_cvt_pk_f16_f32 v85, v108, v109
	v_cvt_pk_f16_f32 v103, v110, v111
	v_add_u32_e32 v74, 0x2000, v72
	global_store_dwordx4 v74, v[82:85], s[76:77]
	global_store_dwordx4 v74, v[100:103], s[78:79]
	s_nop 1
	v_add_u32_e32 v68, 0x600, v154
	v_bfrev_b32_e32 v66, v68
	v_lshrrev_b32_e32 v66, 20, v66
	v_and_b32_e32 v67, 0xaaa, v66
	v_and_b32_e32 v66, 0x555, v66
	v_lshrrev_b32_e32 v67, 1, v67
	v_lshl_or_b32 v69, v66, 1, v67
	v_sub_u32_e32 v69, 0x1000, v69
	v_and_b32_e32 v69, 0xfff, v69
	v_bfrev_b32_e32 v66, v69
	v_lshrrev_b32_e32 v66, 20, v66
	v_and_b32_e32 v67, 0xaaa, v66
	v_and_b32_e32 v66, 0x555, v66
	v_lshrrev_b32_e32 v67, 1, v67
	v_lshl_or_b32 v68, v66, 1, v67
	v_lshlrev_b32_e32 v73, 5, v68
	ds_read_b128 v[20:23], v70 offset:49152
	ds_read_b128 v[24:27], v70 offset:49168
	ds_read_b128 v[58:61], v73
	ds_read_b128 v[62:65], v73 offset:16
	s_waitcnt lgkmcnt(4)
; HD int rev4_14(int p){ unsigned r = __brev((unsigned)p) >> 18; return (int)(((r & 0x2AAAu) >> 1) | ((r & 0x1555u) << 1)); }
; __device__ __forceinline__ void phase_hyena(KP kp_, int hf){ asm volatile("" : "+s"(kp_)); const Params p=load_params(kp_);
;     ...
;     _Pragma("unroll 2") for (int i=0;i<8;++i){ int q0=(tid+512*i)*4; u32x4 h0w, h1w;
;       _Pragma("unroll") for (int m=0;m<4;++m){ int q=q0+m; int k=rev4_14(q);
;         float2 Fk=Z[q], Fn=Z[rev4_14((16384-k)&16383)];
;         f16x2 h0v={(_Float16)(0.5f*nrm0*(Fk.x+Fn.x)),(_Float16)(0.5f*nrm0*(Fk.y-Fn.y))};
;         f16x2 h1v={(_Float16)(0.5f*nrm1*(Fk.y+Fn.y)),(_Float16)(-0.5f*nrm1*(Fk.x-Fn.x))};
;         unsigned u0=__builtin_bit_cast(unsigned,h0v), u1=__builtin_bit_cast(unsigned,h1v);
;         h0w[m]=u0; h1w[m]=u1; }
;       *(u32x4*)(H0p+q0)=h0w; *(u32x4*)(H1p+q0)=h1w; }
	v_pk_add_f32 v[104:105], v[4:5], v[18:19]
	v_pk_add_f32 v[106:107], v[4:5], v[18:19] neg_lo:[0,1] neg_hi:[0,1]
	v_mul_f32_e32 v108, v2, v104
	v_mul_f32_e32 v109, v2, v107
	v_mul_f32_e32 v110, v0, v105
	v_mul_f32_e32 v111, v1, v106
	v_cvt_pk_f16_f32 v82, v108, v109
	v_cvt_pk_f16_f32 v100, v110, v111
	v_pk_add_f32 v[104:105], v[6:7], v[16:17]
	v_pk_add_f32 v[106:107], v[6:7], v[16:17] neg_lo:[0,1] neg_hi:[0,1]
	v_mul_f32_e32 v108, v2, v104
	v_mul_f32_e32 v109, v2, v107
	v_mul_f32_e32 v110, v0, v105
	v_mul_f32_e32 v111, v1, v106
	v_cvt_pk_f16_f32 v83, v108, v109
	v_cvt_pk_f16_f32 v101, v110, v111
	v_pk_add_f32 v[104:105], v[8:9], v[14:15]
	v_pk_add_f32 v[106:107], v[8:9], v[14:15] neg_lo:[0,1] neg_hi:[0,1]
	v_mul_f32_e32 v108, v2, v104
	v_mul_f32_e32 v109, v2, v107
	v_mul_f32_e32 v110, v0, v105
	v_mul_f32_e32 v111, v1, v106
	v_cvt_pk_f16_f32 v84, v108, v109
	v_cvt_pk_f16_f32 v102, v110, v111
	v_pk_add_f32 v[104:105], v[10:11], v[12:13]
	v_pk_add_f32 v[106:107], v[10:11], v[12:13] neg_lo:[0,1] neg_hi:[0,1]
	v_mul_f32_e32 v108, v2, v104
	v_mul_f32_e32 v109, v2, v107
	v_mul_f32_e32 v110, v0, v105
	v_mul_f32_e32 v111, v1, v106
	v_cvt_pk_f16_f32 v85, v108, v109
	v_cvt_pk_f16_f32 v103, v110, v111
	v_add_u32_e32 v74, 0x4000, v72
	global_store_dwordx4 v74, v[82:85], s[76:77]
	global_store_dwordx4 v74, v[100:103], s[78:79]
	s_nop 1
	v_add_u32_e32 v68, 0x800, v154
	v_bfrev_b32_e32 v66, v68
	v_lshrrev_b32_e32 v66, 20, v66
	v_and_b32_e32 v67, 0xaaa, v66
	v_and_b32_e32 v66, 0x555, v66
	v_lshrrev_b32_e32 v67, 1, v67
	v_lshl_or_b32 v69, v66, 1, v67
	v_sub_u32_e32 v69, 0x1000, v69
	v_and_b32_e32 v69, 0xfff, v69
	v_bfrev_b32_e32 v66, v69
	v_lshrrev_b32_e32 v66, 20, v66
	v_and_b32_e32 v67, 0xaaa, v66
	v_and_b32_e32 v66, 0x555, v66
	v_lshrrev_b32_e32 v67, 1, v67
	v_lshl_or_b32 v68, v66, 1, v67
	v_lshlrev_b32_e32 v73, 5, v68
	ds_read_b128 v[4:7], v71 offset:0
	ds_read_b128 v[8:11], v71 offset:16
	ds_read_b128 v[12:15], v73
	ds_read_b128 v[16:19], v73 offset:16
	s_waitcnt lgkmcnt(4)
	v_pk_add_f32 v[104:105], v[20:21], v[64:65]
	v_pk_add_f32 v[106:107], v[20:21], v[64:65] neg_lo:[0,1] neg_hi:[0,1]
	v_mul_f32_e32 v108, v2, v104
	v_mul_f32_e32 v109, v2, v107
	v_mul_f32_e32 v110, v0, v105
	v_mul_f32_e32 v111, v1, v106
	v_cvt_pk_f16_f32 v82, v108, v109
	v_cvt_pk_f16_f32 v100, v110, v111
	v_pk_add_f32 v[104:105], v[22:23], v[62:63]
	v_pk_add_f32 v[106:107], v[22:23], v[62:63] neg_lo:[0,1] neg_hi:[0,1]
	v_mul_f32_e32 v108, v2, v104
	v_mul_f32_e32 v109, v2, v107
	v_mul_f32_e32 v110, v0, v105
	v_mul_f32_e32 v111, v1, v106
	v_cvt_pk_f16_f32 v83, v108, v109
	v_cvt_pk_f16_f32 v101, v110, v111
	v_pk_add_f32 v[104:105], v[24:25], v[60:61]
	v_pk_add_f32 v[106:107], v[24:25], v[60:61] neg_lo:[0,1] neg_hi:[0,1]
	v_mul_f32_e32 v108, v2, v104
	v_mul_f32_e32 v109, v2, v107
	v_mul_f32_e32 v110, v0, v105
	v_mul_f32_e32 v111, v1, v106
	v_cvt_pk_f16_f32 v84, v108, v109
	v_cvt_pk_f16_f32 v102, v110, v111
	v_pk_add_f32 v[104:105], v[26:27], v[58:59]
	v_pk_add_f32 v[106:107], v[26:27], v[58:59] neg_lo:[0,1] neg_hi:[0,1]
	v_mul_f32_e32 v108, v2, v104
	v_mul_f32_e32 v109, v2, v107
	v_mul_f32_e32 v110, v0, v105
	v_mul_f32_e32 v111, v1, v106
	v_cvt_pk_f16_f32 v85, v108, v109
	v_cvt_pk_f16_f32 v103, v110, v111
	v_add_u32_e32 v74, 0x6000, v72
	global_store_dwordx4 v74, v[82:85], s[76:77]
	global_store_dwordx4 v74, v[100:103], s[78:79]
	s_nop 1
	v_add_u32_e32 v68, 0xa00, v154
	v_bfrev_b32_e32 v66, v68
	v_lshrrev_b32_e32 v66, 20, v66
	v_and_b32_e32 v67, 0xaaa, v66
	v_and_b32_e32 v66, 0x555, v66
	v_lshrrev_b32_e32 v67, 1, v67
	v_lshl_or_b32 v69, v66, 1, v67
	v_sub_u32_e32 v69, 0x1000, v69
	v_and_b32_e32 v69, 0xfff, v69
	v_bfrev_b32_e32 v66, v69
	v_lshrrev_b32_e32 v66, 20, v66
	v_and_b32_e32 v67, 0xaaa, v66
	v_and_b32_e32 v66, 0x555, v66
	v_lshrrev_b32_e32 v67, 1, v67
	v_lshl_or_b32 v68, v66, 1, v67
	v_lshlrev_b32_e32 v73, 5, v68
	ds_read_b128 v[20:23], v71 offset:16384
	ds_read_b128 v[24:27], v71 offset:16400
	ds_read_b128 v[58:61], v73
	ds_read_b128 v[62:65], v73 offset:16
	s_waitcnt lgkmcnt(4)
	v_pk_add_f32 v[104:105], v[4:5], v[18:19]
	v_pk_add_f32 v[106:107], v[4:5], v[18:19] neg_lo:[0,1] neg_hi:[0,1]
	v_mul_f32_e32 v108, v2, v104
	v_mul_f32_e32 v109, v2, v107
	v_mul_f32_e32 v110, v0, v105
	v_mul_f32_e32 v111, v1, v106
	v_cvt_pk_f16_f32 v82, v108, v109
	v_cvt_pk_f16_f32 v100, v110, v111
	v_pk_add_f32 v[104:105], v[6:7], v[16:17]
	v_pk_add_f32 v[106:107], v[6:7], v[16:17] neg_lo:[0,1] neg_hi:[0,1]
	v_mul_f32_e32 v108, v2, v104
	v_mul_f32_e32 v109, v2, v107
	v_mul_f32_e32 v110, v0, v105
	v_mul_f32_e32 v111, v1, v106
	v_cvt_pk_f16_f32 v83, v108, v109
	v_cvt_pk_f16_f32 v101, v110, v111
	v_pk_add_f32 v[104:105], v[8:9], v[14:15]
	v_pk_add_f32 v[106:107], v[8:9], v[14:15] neg_lo:[0,1] neg_hi:[0,1]
	v_mul_f32_e32 v108, v2, v104
	v_mul_f32_e32 v109, v2, v107
	v_mul_f32_e32 v110, v0, v105
	v_mul_f32_e32 v111, v1, v106
	v_cvt_pk_f16_f32 v84, v108, v109
	v_cvt_pk_f16_f32 v102, v110, v111
	v_pk_add_f32 v[104:105], v[10:11], v[12:13]
	v_pk_add_f32 v[106:107], v[10:11], v[12:13] neg_lo:[0,1] neg_hi:[0,1]
	v_mul_f32_e32 v108, v2, v104
	v_mul_f32_e32 v109, v2, v107
	v_mul_f32_e32 v110, v0, v105
	v_mul_f32_e32 v111, v1, v106
	v_cvt_pk_f16_f32 v85, v108, v109
	v_cvt_pk_f16_f32 v103, v110, v111
	v_add_u32_e32 v74, 0x8000, v72
	global_store_dwordx4 v74, v[82:85], s[76:77]
	global_store_dwordx4 v74, v[100:103], s[78:79]
	s_nop 1
	v_add_u32_e32 v68, 0xc00, v154
	v_bfrev_b32_e32 v66, v68
	v_lshrrev_b32_e32 v66, 20, v66
	v_and_b32_e32 v67, 0xaaa, v66
	v_and_b32_e32 v66, 0x555, v66
	v_lshrrev_b32_e32 v67, 1, v67
	v_lshl_or_b32 v69, v66, 1, v67
	v_sub_u32_e32 v69, 0x1000, v69
	v_and_b32_e32 v69, 0xfff, v69
	v_bfrev_b32_e32 v66, v69
	v_lshrrev_b32_e32 v66, 20, v66
	v_and_b32_e32 v67, 0xaaa, v66
	v_and_b32_e32 v66, 0x555, v66
	v_lshrrev_b32_e32 v67, 1, v67
	v_lshl_or_b32 v68, v66, 1, v67
	v_lshlrev_b32_e32 v73, 5, v68
	ds_read_b128 v[4:7], v71 offset:32768
	ds_read_b128 v[8:11], v71 offset:32784
	ds_read_b128 v[12:15], v73
	ds_read_b128 v[16:19], v73 offset:16
	s_waitcnt lgkmcnt(4)
; HD int rev4_14(int p){ unsigned r = __brev((unsigned)p) >> 18; return (int)(((r & 0x2AAAu) >> 1) | ((r & 0x1555u) << 1)); }
; __device__ __forceinline__ void phase_hyena(KP kp_, int hf){ asm volatile("" : "+s"(kp_)); const Params p=load_params(kp_);
;     ...
;     _Pragma("unroll 2") for (int i=0;i<8;++i){ int q0=(tid+512*i)*4; u32x4 h0w, h1w;
;       _Pragma("unroll") for (int m=0;m<4;++m){ int q=q0+m; int k=rev4_14(q);
;         float2 Fk=Z[q], Fn=Z[rev4_14((16384-k)&16383)];
;         f16x2 h0v={(_Float16)(0.5f*nrm0*(Fk.x+Fn.x)),(_Float16)(0.5f*nrm0*(Fk.y-Fn.y))};
;         f16x2 h1v={(_Float16)(0.5f*nrm1*(Fk.y+Fn.y)),(_Float16)(-0.5f*nrm1*(Fk.x-Fn.x))};
;         unsigned u0=__builtin_bit_cast(unsigned,h0v), u1=__builtin_bit_cast(unsigned,h1v);
;         h0w[m]=u0; h1w[m]=u1; }
;       *(u32x4*)(H0p+q0)=h0w; *(u32x4*)(H1p+q0)=h1w; }
;         __builtin_amdgcn_fence(__ATOMIC_ACQUIRE, "agent");
	v_pk_add_f32 v[104:105], v[20:21], v[64:65]
	v_pk_add_f32 v[106:107], v[20:21], v[64:65] neg_lo:[0,1] neg_hi:[0,1]
	v_mul_f32_e32 v108, v2, v104
	v_mul_f32_e32 v109, v2, v107
	v_mul_f32_e32 v110, v0, v105
	v_mul_f32_e32 v111, v1, v106
	v_cvt_pk_f16_f32 v82, v108, v109
	v_cvt_pk_f16_f32 v100, v110, v111
	v_pk_add_f32 v[104:105], v[22:23], v[62:63]
	v_pk_add_f32 v[106:107], v[22:23], v[62:63] neg_lo:[0,1] neg_hi:[0,1]
	v_mul_f32_e32 v108, v2, v104
	v_mul_f32_e32 v109, v2, v107
	v_mul_f32_e32 v110, v0, v105
	v_mul_f32_e32 v111, v1, v106
	v_cvt_pk_f16_f32 v83, v108, v109
	v_cvt_pk_f16_f32 v101, v110, v111
	v_pk_add_f32 v[104:105], v[24:25], v[60:61]
	v_pk_add_f32 v[106:107], v[24:25], v[60:61] neg_lo:[0,1] neg_hi:[0,1]
	v_mul_f32_e32 v108, v2, v104
	v_mul_f32_e32 v109, v2, v107
	v_mul_f32_e32 v110, v0, v105
	v_mul_f32_e32 v111, v1, v106
	v_cvt_pk_f16_f32 v84, v108, v109
	v_cvt_pk_f16_f32 v102, v110, v111
	v_pk_add_f32 v[104:105], v[26:27], v[58:59]
	v_pk_add_f32 v[106:107], v[26:27], v[58:59] neg_lo:[0,1] neg_hi:[0,1]
	v_mul_f32_e32 v108, v2, v104
	v_mul_f32_e32 v109, v2, v107
	v_mul_f32_e32 v110, v0, v105
	v_mul_f32_e32 v111, v1, v106
	v_cvt_pk_f16_f32 v85, v108, v109
	v_cvt_pk_f16_f32 v103, v110, v111
	v_add_u32_e32 v74, 0xa000, v72
	global_store_dwordx4 v74, v[82:85], s[76:77]
	global_store_dwordx4 v74, v[100:103], s[78:79]
	s_nop 1
	v_add_u32_e32 v68, 0xe00, v154
	v_bfrev_b32_e32 v66, v68
	v_lshrrev_b32_e32 v66, 20, v66
	v_and_b32_e32 v67, 0xaaa, v66
	v_and_b32_e32 v66, 0x555, v66
	v_lshrrev_b32_e32 v67, 1, v67
	v_lshl_or_b32 v69, v66, 1, v67
	v_sub_u32_e32 v69, 0x1000, v69
	v_and_b32_e32 v69, 0xfff, v69
	v_bfrev_b32_e32 v66, v69
	v_lshrrev_b32_e32 v66, 20, v66
	v_and_b32_e32 v67, 0xaaa, v66
	v_and_b32_e32 v66, 0x555, v66
	v_lshrrev_b32_e32 v67, 1, v67
	v_lshl_or_b32 v68, v66, 1, v67
	v_lshlrev_b32_e32 v73, 5, v68
	ds_read_b128 v[20:23], v71 offset:49152
	ds_read_b128 v[24:27], v71 offset:49168
	ds_read_b128 v[58:61], v73
	ds_read_b128 v[62:65], v73 offset:16
	s_waitcnt lgkmcnt(4)
	v_pk_add_f32 v[104:105], v[4:5], v[18:19]
	v_pk_add_f32 v[106:107], v[4:5], v[18:19] neg_lo:[0,1] neg_hi:[0,1]
	v_mul_f32_e32 v108, v2, v104
	v_mul_f32_e32 v109, v2, v107
	v_mul_f32_e32 v110, v0, v105
	v_mul_f32_e32 v111, v1, v106
	v_cvt_pk_f16_f32 v82, v108, v109
	v_cvt_pk_f16_f32 v100, v110, v111
	v_pk_add_f32 v[104:105], v[6:7], v[16:17]
	v_pk_add_f32 v[106:107], v[6:7], v[16:17] neg_lo:[0,1] neg_hi:[0,1]
	v_mul_f32_e32 v108, v2, v104
	v_mul_f32_e32 v109, v2, v107
	v_mul_f32_e32 v110, v0, v105
	v_mul_f32_e32 v111, v1, v106
	v_cvt_pk_f16_f32 v83, v108, v109
	v_cvt_pk_f16_f32 v101, v110, v111
	v_pk_add_f32 v[104:105], v[8:9], v[14:15]
	v_pk_add_f32 v[106:107], v[8:9], v[14:15] neg_lo:[0,1] neg_hi:[0,1]
	v_mul_f32_e32 v108, v2, v104
	v_mul_f32_e32 v109, v2, v107
	v_mul_f32_e32 v110, v0, v105
	v_mul_f32_e32 v111, v1, v106
	v_cvt_pk_f16_f32 v84, v108, v109
	v_cvt_pk_f16_f32 v102, v110, v111
	v_pk_add_f32 v[104:105], v[10:11], v[12:13]
	v_pk_add_f32 v[106:107], v[10:11], v[12:13] neg_lo:[0,1] neg_hi:[0,1]
	v_mul_f32_e32 v108, v2, v104
	v_mul_f32_e32 v109, v2, v107
	v_mul_f32_e32 v110, v0, v105
	v_mul_f32_e32 v111, v1, v106
	v_cvt_pk_f16_f32 v85, v108, v109
	v_cvt_pk_f16_f32 v103, v110, v111
	v_add_u32_e32 v74, 0xc000, v72
	global_store_dwordx4 v74, v[82:85], s[76:77]
	global_store_dwordx4 v74, v[100:103], s[78:79]
	s_nop 1
	s_waitcnt lgkmcnt(0)
	v_pk_add_f32 v[104:105], v[20:21], v[64:65]
	v_pk_add_f32 v[106:107], v[20:21], v[64:65] neg_lo:[0,1] neg_hi:[0,1]
	v_mul_f32_e32 v108, v2, v104
	v_mul_f32_e32 v109, v2, v107
	v_mul_f32_e32 v110, v0, v105
	v_mul_f32_e32 v111, v1, v106
	v_cvt_pk_f16_f32 v82, v108, v109
	v_cvt_pk_f16_f32 v100, v110, v111
	v_pk_add_f32 v[104:105], v[22:23], v[62:63]
	v_pk_add_f32 v[106:107], v[22:23], v[62:63] neg_lo:[0,1] neg_hi:[0,1]
	v_mul_f32_e32 v108, v2, v104
	v_mul_f32_e32 v109, v2, v107
	v_mul_f32_e32 v110, v0, v105
	v_mul_f32_e32 v111, v1, v106
	v_cvt_pk_f16_f32 v83, v108, v109
	v_cvt_pk_f16_f32 v101, v110, v111
	v_pk_add_f32 v[104:105], v[24:25], v[60:61]
	v_pk_add_f32 v[106:107], v[24:25], v[60:61] neg_lo:[0,1] neg_hi:[0,1]
	v_mul_f32_e32 v108, v2, v104
	v_mul_f32_e32 v109, v2, v107
	v_mul_f32_e32 v110, v0, v105
	v_mul_f32_e32 v111, v1, v106
	v_cvt_pk_f16_f32 v84, v108, v109
	v_cvt_pk_f16_f32 v102, v110, v111
	v_pk_add_f32 v[104:105], v[26:27], v[58:59]
	v_pk_add_f32 v[106:107], v[26:27], v[58:59] neg_lo:[0,1] neg_hi:[0,1]
	v_mul_f32_e32 v108, v2, v104
	v_mul_f32_e32 v109, v2, v107
	v_mul_f32_e32 v110, v0, v105
	v_mul_f32_e32 v111, v1, v106
	v_cvt_pk_f16_f32 v85, v108, v109
	v_cvt_pk_f16_f32 v103, v110, v111
	v_add_u32_e32 v74, 0xe000, v72
	global_store_dwordx4 v74, v[82:85], s[76:77]
	global_store_dwordx4 v74, v[100:103], s[78:79]
	s_nop 1
	s_waitcnt vmcnt(0) lgkmcnt(0)
	buffer_inv sc1
	s_branch .LBB0_1198
